# triangular substitution fetches several rows of the transposed system per LDS round trip (12 round trips instead of 31), full waits before arithmetic
# baseline (speedup 1.0000x reference)
.Ldc_b2:
	s_waitcnt lgkmcnt(0)
	s_barrier
	s_cmp_ge_u32 s60, 2
	s_cbranch_scc1 .Ldc_s2q
	s_cmp_eq_u32 s60, 1
	s_cbranch_scc1 .Ldc_s2k
	v_and_b32_e32 v135, 31, v221
	v_lshlrev_b32_e32 v135, 2, v135
	ds_read_b32 v10, v135 offset:57856
	ds_read_b32 v11, v135 offset:58000
	ds_read_b32 v12, v135 offset:58144
	ds_read_b32 v13, v135 offset:58288
	ds_read_b32 v14, v135 offset:58432
	ds_read_b32 v15, v135 offset:58576
	ds_read_b32 v16, v135 offset:58720
	ds_read_b32 v17, v135 offset:58864
	ds_read_b32 v18, v135 offset:59008
	ds_read_b32 v19, v135 offset:59152
	ds_read_b32 v20, v135 offset:59296
	ds_read_b32 v21, v135 offset:59440
	ds_read_b32 v22, v135 offset:59584
	ds_read_b32 v23, v135 offset:59728
	ds_read_b32 v24, v135 offset:59872
	ds_read_b32 v25, v135 offset:60016
	ds_read_b32 v26, v135 offset:60160
	ds_read_b32 v27, v135 offset:60304
	ds_read_b32 v28, v135 offset:60448
	ds_read_b32 v29, v135 offset:60592
	ds_read_b32 v30, v135 offset:60736
	ds_read_b32 v31, v135 offset:60880
	ds_read_b32 v32, v135 offset:61024
	ds_read_b32 v33, v135 offset:61168
	ds_read_b32 v34, v135 offset:61312
	ds_read_b32 v35, v135 offset:61456
	ds_read_b32 v36, v135 offset:61600
	ds_read_b32 v37, v135 offset:61744
	ds_read_b32 v38, v135 offset:61888
	ds_read_b32 v39, v135 offset:62032
	ds_read_b32 v40, v135 offset:62176
	ds_read_b32 v41, v135 offset:62320
	ds_read_b128 v[42:45], v1 offset:44032
	ds_read_b128 v[46:49], v1 offset:44048
	ds_read_b128 v[50:53], v1 offset:44064
	ds_read_b128 v[54:57], v1 offset:44080
	ds_read_b128 v[58:61], v1 offset:44096
	ds_read_b128 v[62:65], v1 offset:44112
	ds_read_b128 v[66:69], v1 offset:44128
	ds_read_b128 v[70:73], v1 offset:44144
	s_waitcnt lgkmcnt(0)
	v_fmac_f32_e32 v11, v43, v10
	v_pk_fma_f32 v[12:13], v[44:45], v[10:11], v[12:13] op_sel:[0,0,0] op_sel_hi:[1,0,1]
	v_pk_fma_f32 v[14:15], v[46:47], v[10:11], v[14:15] op_sel:[0,0,0] op_sel_hi:[1,0,1]
	v_pk_fma_f32 v[16:17], v[48:49], v[10:11], v[16:17] op_sel:[0,0,0] op_sel_hi:[1,0,1]
	v_pk_fma_f32 v[18:19], v[50:51], v[10:11], v[18:19] op_sel:[0,0,0] op_sel_hi:[1,0,1]
	v_pk_fma_f32 v[20:21], v[52:53], v[10:11], v[20:21] op_sel:[0,0,0] op_sel_hi:[1,0,1]
	v_pk_fma_f32 v[22:23], v[54:55], v[10:11], v[22:23] op_sel:[0,0,0] op_sel_hi:[1,0,1]
	v_pk_fma_f32 v[24:25], v[56:57], v[10:11], v[24:25] op_sel:[0,0,0] op_sel_hi:[1,0,1]
	v_pk_fma_f32 v[26:27], v[58:59], v[10:11], v[26:27] op_sel:[0,0,0] op_sel_hi:[1,0,1]
	v_pk_fma_f32 v[28:29], v[60:61], v[10:11], v[28:29] op_sel:[0,0,0] op_sel_hi:[1,0,1]
	v_pk_fma_f32 v[30:31], v[62:63], v[10:11], v[30:31] op_sel:[0,0,0] op_sel_hi:[1,0,1]
	v_pk_fma_f32 v[32:33], v[64:65], v[10:11], v[32:33] op_sel:[0,0,0] op_sel_hi:[1,0,1]
	v_pk_fma_f32 v[34:35], v[66:67], v[10:11], v[34:35] op_sel:[0,0,0] op_sel_hi:[1,0,1]
	v_pk_fma_f32 v[36:37], v[68:69], v[10:11], v[36:37] op_sel:[0,0,0] op_sel_hi:[1,0,1]
	v_pk_fma_f32 v[38:39], v[70:71], v[10:11], v[38:39] op_sel:[0,0,0] op_sel_hi:[1,0,1]
	v_pk_fma_f32 v[40:41], v[72:73], v[10:11], v[40:41] op_sel:[0,0,0] op_sel_hi:[1,0,1]
	ds_read_b128 v[42:45], v1 offset:44176
	ds_read_b128 v[46:49], v1 offset:44192
	ds_read_b128 v[50:53], v1 offset:44208
	ds_read_b128 v[54:57], v1 offset:44224
	ds_read_b128 v[58:61], v1 offset:44240
	ds_read_b128 v[62:65], v1 offset:44256
	ds_read_b128 v[66:69], v1 offset:44272
	ds_read_b128 v[70:73], v1 offset:44288
	s_waitcnt lgkmcnt(0)
	v_pk_fma_f32 v[12:13], v[44:45], v[10:11], v[12:13] op_sel:[0,1,0] op_sel_hi:[1,1,1]
	v_pk_fma_f32 v[14:15], v[46:47], v[10:11], v[14:15] op_sel:[0,1,0] op_sel_hi:[1,1,1]
	v_pk_fma_f32 v[16:17], v[48:49], v[10:11], v[16:17] op_sel:[0,1,0] op_sel_hi:[1,1,1]
	v_pk_fma_f32 v[18:19], v[50:51], v[10:11], v[18:19] op_sel:[0,1,0] op_sel_hi:[1,1,1]
	v_pk_fma_f32 v[20:21], v[52:53], v[10:11], v[20:21] op_sel:[0,1,0] op_sel_hi:[1,1,1]
	v_pk_fma_f32 v[22:23], v[54:55], v[10:11], v[22:23] op_sel:[0,1,0] op_sel_hi:[1,1,1]
	v_pk_fma_f32 v[24:25], v[56:57], v[10:11], v[24:25] op_sel:[0,1,0] op_sel_hi:[1,1,1]
	v_pk_fma_f32 v[26:27], v[58:59], v[10:11], v[26:27] op_sel:[0,1,0] op_sel_hi:[1,1,1]
	v_pk_fma_f32 v[28:29], v[60:61], v[10:11], v[28:29] op_sel:[0,1,0] op_sel_hi:[1,1,1]
	v_pk_fma_f32 v[30:31], v[62:63], v[10:11], v[30:31] op_sel:[0,1,0] op_sel_hi:[1,1,1]
	v_pk_fma_f32 v[32:33], v[64:65], v[10:11], v[32:33] op_sel:[0,1,0] op_sel_hi:[1,1,1]
	v_pk_fma_f32 v[34:35], v[66:67], v[10:11], v[34:35] op_sel:[0,1,0] op_sel_hi:[1,1,1]
	v_pk_fma_f32 v[36:37], v[68:69], v[10:11], v[36:37] op_sel:[0,1,0] op_sel_hi:[1,1,1]
	v_pk_fma_f32 v[38:39], v[70:71], v[10:11], v[38:39] op_sel:[0,1,0] op_sel_hi:[1,1,1]
	v_pk_fma_f32 v[40:41], v[72:73], v[10:11], v[40:41] op_sel:[0,1,0] op_sel_hi:[1,1,1]
	ds_read_b128 v[42:45], v1 offset:44320
	ds_read_b128 v[46:49], v1 offset:44336
	ds_read_b128 v[50:53], v1 offset:44352
	ds_read_b128 v[54:57], v1 offset:44368
	ds_read_b128 v[58:61], v1 offset:44384
	ds_read_b128 v[62:65], v1 offset:44400
	ds_read_b128 v[66:69], v1 offset:44416
	ds_read_b128 v[70:73], v1 offset:44432
	ds_read_b128 v[74:77], v1 offset:44480
	ds_read_b128 v[78:81], v1 offset:44496
	ds_read_b128 v[82:85], v1 offset:44512
	ds_read_b128 v[86:89], v1 offset:44528
	ds_read_b128 v[226:229], v1 offset:44544
	ds_read_b128 v[230:233], v1 offset:44560
	ds_read_b128 v[234:237], v1 offset:44576
	s_waitcnt lgkmcnt(0)
	v_fmac_f32_e32 v13, v45, v12
	v_pk_fma_f32 v[14:15], v[46:47], v[12:13], v[14:15] op_sel:[0,0,0] op_sel_hi:[1,0,1]
	v_pk_fma_f32 v[16:17], v[48:49], v[12:13], v[16:17] op_sel:[0,0,0] op_sel_hi:[1,0,1]
	v_pk_fma_f32 v[18:19], v[50:51], v[12:13], v[18:19] op_sel:[0,0,0] op_sel_hi:[1,0,1]
	v_pk_fma_f32 v[20:21], v[52:53], v[12:13], v[20:21] op_sel:[0,0,0] op_sel_hi:[1,0,1]
	v_pk_fma_f32 v[22:23], v[54:55], v[12:13], v[22:23] op_sel:[0,0,0] op_sel_hi:[1,0,1]
	v_pk_fma_f32 v[24:25], v[56:57], v[12:13], v[24:25] op_sel:[0,0,0] op_sel_hi:[1,0,1]
	v_pk_fma_f32 v[26:27], v[58:59], v[12:13], v[26:27] op_sel:[0,0,0] op_sel_hi:[1,0,1]
	v_pk_fma_f32 v[28:29], v[60:61], v[12:13], v[28:29] op_sel:[0,0,0] op_sel_hi:[1,0,1]
	v_pk_fma_f32 v[30:31], v[62:63], v[12:13], v[30:31] op_sel:[0,0,0] op_sel_hi:[1,0,1]
	v_pk_fma_f32 v[32:33], v[64:65], v[12:13], v[32:33] op_sel:[0,0,0] op_sel_hi:[1,0,1]
	v_pk_fma_f32 v[34:35], v[66:67], v[12:13], v[34:35] op_sel:[0,0,0] op_sel_hi:[1,0,1]
	v_pk_fma_f32 v[36:37], v[68:69], v[12:13], v[36:37] op_sel:[0,0,0] op_sel_hi:[1,0,1]
	v_pk_fma_f32 v[38:39], v[70:71], v[12:13], v[38:39] op_sel:[0,0,0] op_sel_hi:[1,0,1]
	v_pk_fma_f32 v[40:41], v[72:73], v[12:13], v[40:41] op_sel:[0,0,0] op_sel_hi:[1,0,1]
	v_pk_fma_f32 v[14:15], v[74:75], v[12:13], v[14:15] op_sel:[0,1,0] op_sel_hi:[1,1,1]
	v_pk_fma_f32 v[16:17], v[76:77], v[12:13], v[16:17] op_sel:[0,1,0] op_sel_hi:[1,1,1]
	v_pk_fma_f32 v[18:19], v[78:79], v[12:13], v[18:19] op_sel:[0,1,0] op_sel_hi:[1,1,1]
	v_pk_fma_f32 v[20:21], v[80:81], v[12:13], v[20:21] op_sel:[0,1,0] op_sel_hi:[1,1,1]
	v_pk_fma_f32 v[22:23], v[82:83], v[12:13], v[22:23] op_sel:[0,1,0] op_sel_hi:[1,1,1]
	v_pk_fma_f32 v[24:25], v[84:85], v[12:13], v[24:25] op_sel:[0,1,0] op_sel_hi:[1,1,1]
	v_pk_fma_f32 v[26:27], v[86:87], v[12:13], v[26:27] op_sel:[0,1,0] op_sel_hi:[1,1,1]
	v_pk_fma_f32 v[28:29], v[88:89], v[12:13], v[28:29] op_sel:[0,1,0] op_sel_hi:[1,1,1]
	v_pk_fma_f32 v[30:31], v[226:227], v[12:13], v[30:31] op_sel:[0,1,0] op_sel_hi:[1,1,1]
	v_pk_fma_f32 v[32:33], v[228:229], v[12:13], v[32:33] op_sel:[0,1,0] op_sel_hi:[1,1,1]
	v_pk_fma_f32 v[34:35], v[230:231], v[12:13], v[34:35] op_sel:[0,1,0] op_sel_hi:[1,1,1]
	v_pk_fma_f32 v[36:37], v[232:233], v[12:13], v[36:37] op_sel:[0,1,0] op_sel_hi:[1,1,1]
	v_pk_fma_f32 v[38:39], v[234:235], v[12:13], v[38:39] op_sel:[0,1,0] op_sel_hi:[1,1,1]
	v_pk_fma_f32 v[40:41], v[236:237], v[12:13], v[40:41] op_sel:[0,1,0] op_sel_hi:[1,1,1]
	ds_read_b128 v[42:45], v1 offset:44624
	ds_read_b128 v[46:49], v1 offset:44640
	ds_read_b128 v[50:53], v1 offset:44656
	ds_read_b128 v[54:57], v1 offset:44672
	ds_read_b128 v[58:61], v1 offset:44688
	ds_read_b128 v[62:65], v1 offset:44704
	ds_read_b128 v[66:69], v1 offset:44720
	ds_read_b128 v[70:73], v1 offset:44768
	ds_read_b128 v[74:77], v1 offset:44784
	ds_read_b128 v[78:81], v1 offset:44800
	ds_read_b128 v[82:85], v1 offset:44816
	ds_read_b128 v[86:89], v1 offset:44832
	ds_read_b128 v[226:229], v1 offset:44848
	ds_read_b128 v[230:233], v1 offset:44864
	s_waitcnt lgkmcnt(0)
	v_fmac_f32_e32 v15, v43, v14
	v_pk_fma_f32 v[16:17], v[44:45], v[14:15], v[16:17] op_sel:[0,0,0] op_sel_hi:[1,0,1]
	v_pk_fma_f32 v[18:19], v[46:47], v[14:15], v[18:19] op_sel:[0,0,0] op_sel_hi:[1,0,1]
	v_pk_fma_f32 v[20:21], v[48:49], v[14:15], v[20:21] op_sel:[0,0,0] op_sel_hi:[1,0,1]
	v_pk_fma_f32 v[22:23], v[50:51], v[14:15], v[22:23] op_sel:[0,0,0] op_sel_hi:[1,0,1]
	v_pk_fma_f32 v[24:25], v[52:53], v[14:15], v[24:25] op_sel:[0,0,0] op_sel_hi:[1,0,1]
	v_pk_fma_f32 v[26:27], v[54:55], v[14:15], v[26:27] op_sel:[0,0,0] op_sel_hi:[1,0,1]
	v_pk_fma_f32 v[28:29], v[56:57], v[14:15], v[28:29] op_sel:[0,0,0] op_sel_hi:[1,0,1]
	v_pk_fma_f32 v[30:31], v[58:59], v[14:15], v[30:31] op_sel:[0,0,0] op_sel_hi:[1,0,1]
	v_pk_fma_f32 v[32:33], v[60:61], v[14:15], v[32:33] op_sel:[0,0,0] op_sel_hi:[1,0,1]
	v_pk_fma_f32 v[34:35], v[62:63], v[14:15], v[34:35] op_sel:[0,0,0] op_sel_hi:[1,0,1]
	v_pk_fma_f32 v[36:37], v[64:65], v[14:15], v[36:37] op_sel:[0,0,0] op_sel_hi:[1,0,1]
	v_pk_fma_f32 v[38:39], v[66:67], v[14:15], v[38:39] op_sel:[0,0,0] op_sel_hi:[1,0,1]
	v_pk_fma_f32 v[40:41], v[68:69], v[14:15], v[40:41] op_sel:[0,0,0] op_sel_hi:[1,0,1]
	v_pk_fma_f32 v[16:17], v[72:73], v[14:15], v[16:17] op_sel:[0,1,0] op_sel_hi:[1,1,1]
	v_pk_fma_f32 v[18:19], v[74:75], v[14:15], v[18:19] op_sel:[0,1,0] op_sel_hi:[1,1,1]
	v_pk_fma_f32 v[20:21], v[76:77], v[14:15], v[20:21] op_sel:[0,1,0] op_sel_hi:[1,1,1]
	v_pk_fma_f32 v[22:23], v[78:79], v[14:15], v[22:23] op_sel:[0,1,0] op_sel_hi:[1,1,1]
	v_pk_fma_f32 v[24:25], v[80:81], v[14:15], v[24:25] op_sel:[0,1,0] op_sel_hi:[1,1,1]
	v_pk_fma_f32 v[26:27], v[82:83], v[14:15], v[26:27] op_sel:[0,1,0] op_sel_hi:[1,1,1]
	v_pk_fma_f32 v[28:29], v[84:85], v[14:15], v[28:29] op_sel:[0,1,0] op_sel_hi:[1,1,1]
	v_pk_fma_f32 v[30:31], v[86:87], v[14:15], v[30:31] op_sel:[0,1,0] op_sel_hi:[1,1,1]
	v_pk_fma_f32 v[32:33], v[88:89], v[14:15], v[32:33] op_sel:[0,1,0] op_sel_hi:[1,1,1]
	v_pk_fma_f32 v[34:35], v[226:227], v[14:15], v[34:35] op_sel:[0,1,0] op_sel_hi:[1,1,1]
	v_pk_fma_f32 v[36:37], v[228:229], v[14:15], v[36:37] op_sel:[0,1,0] op_sel_hi:[1,1,1]
	v_pk_fma_f32 v[38:39], v[230:231], v[14:15], v[38:39] op_sel:[0,1,0] op_sel_hi:[1,1,1]
	v_pk_fma_f32 v[40:41], v[232:233], v[14:15], v[40:41] op_sel:[0,1,0] op_sel_hi:[1,1,1]
	ds_read_b128 v[42:45], v1 offset:44912
	ds_read_b128 v[46:49], v1 offset:44928
	ds_read_b128 v[50:53], v1 offset:44944
	ds_read_b128 v[54:57], v1 offset:44960
	ds_read_b128 v[58:61], v1 offset:44976
	ds_read_b128 v[62:65], v1 offset:44992
	ds_read_b128 v[66:69], v1 offset:45008
	ds_read_b128 v[70:73], v1 offset:45072
	ds_read_b128 v[74:77], v1 offset:45088
	ds_read_b128 v[78:81], v1 offset:45104
	ds_read_b128 v[82:85], v1 offset:45120
	ds_read_b128 v[86:89], v1 offset:45136
	ds_read_b128 v[226:229], v1 offset:45152
	s_waitcnt lgkmcnt(0)
	v_fmac_f32_e32 v17, v45, v16
	v_pk_fma_f32 v[18:19], v[46:47], v[16:17], v[18:19] op_sel:[0,0,0] op_sel_hi:[1,0,1]
	v_pk_fma_f32 v[20:21], v[48:49], v[16:17], v[20:21] op_sel:[0,0,0] op_sel_hi:[1,0,1]
	v_pk_fma_f32 v[22:23], v[50:51], v[16:17], v[22:23] op_sel:[0,0,0] op_sel_hi:[1,0,1]
	v_pk_fma_f32 v[24:25], v[52:53], v[16:17], v[24:25] op_sel:[0,0,0] op_sel_hi:[1,0,1]
	v_pk_fma_f32 v[26:27], v[54:55], v[16:17], v[26:27] op_sel:[0,0,0] op_sel_hi:[1,0,1]
	v_pk_fma_f32 v[28:29], v[56:57], v[16:17], v[28:29] op_sel:[0,0,0] op_sel_hi:[1,0,1]
	v_pk_fma_f32 v[30:31], v[58:59], v[16:17], v[30:31] op_sel:[0,0,0] op_sel_hi:[1,0,1]
	v_pk_fma_f32 v[32:33], v[60:61], v[16:17], v[32:33] op_sel:[0,0,0] op_sel_hi:[1,0,1]
	v_pk_fma_f32 v[34:35], v[62:63], v[16:17], v[34:35] op_sel:[0,0,0] op_sel_hi:[1,0,1]
	v_pk_fma_f32 v[36:37], v[64:65], v[16:17], v[36:37] op_sel:[0,0,0] op_sel_hi:[1,0,1]
	v_pk_fma_f32 v[38:39], v[66:67], v[16:17], v[38:39] op_sel:[0,0,0] op_sel_hi:[1,0,1]
	v_pk_fma_f32 v[40:41], v[68:69], v[16:17], v[40:41] op_sel:[0,0,0] op_sel_hi:[1,0,1]
	v_pk_fma_f32 v[18:19], v[70:71], v[16:17], v[18:19] op_sel:[0,1,0] op_sel_hi:[1,1,1]
	v_pk_fma_f32 v[20:21], v[72:73], v[16:17], v[20:21] op_sel:[0,1,0] op_sel_hi:[1,1,1]
	v_pk_fma_f32 v[22:23], v[74:75], v[16:17], v[22:23] op_sel:[0,1,0] op_sel_hi:[1,1,1]
	v_pk_fma_f32 v[24:25], v[76:77], v[16:17], v[24:25] op_sel:[0,1,0] op_sel_hi:[1,1,1]
	v_pk_fma_f32 v[26:27], v[78:79], v[16:17], v[26:27] op_sel:[0,1,0] op_sel_hi:[1,1,1]
	v_pk_fma_f32 v[28:29], v[80:81], v[16:17], v[28:29] op_sel:[0,1,0] op_sel_hi:[1,1,1]
	v_pk_fma_f32 v[30:31], v[82:83], v[16:17], v[30:31] op_sel:[0,1,0] op_sel_hi:[1,1,1]
	v_pk_fma_f32 v[32:33], v[84:85], v[16:17], v[32:33] op_sel:[0,1,0] op_sel_hi:[1,1,1]
	v_pk_fma_f32 v[34:35], v[86:87], v[16:17], v[34:35] op_sel:[0,1,0] op_sel_hi:[1,1,1]
	v_pk_fma_f32 v[36:37], v[88:89], v[16:17], v[36:37] op_sel:[0,1,0] op_sel_hi:[1,1,1]
	v_pk_fma_f32 v[38:39], v[226:227], v[16:17], v[38:39] op_sel:[0,1,0] op_sel_hi:[1,1,1]
	v_pk_fma_f32 v[40:41], v[228:229], v[16:17], v[40:41] op_sel:[0,1,0] op_sel_hi:[1,1,1]
	ds_read_b128 v[42:45], v1 offset:45216
	ds_read_b128 v[46:49], v1 offset:45232
	ds_read_b128 v[50:53], v1 offset:45248
	ds_read_b128 v[54:57], v1 offset:45264
	ds_read_b128 v[58:61], v1 offset:45280
	ds_read_b128 v[62:65], v1 offset:45296
	ds_read_b128 v[66:69], v1 offset:45360
	ds_read_b128 v[70:73], v1 offset:45376
	ds_read_b128 v[74:77], v1 offset:45392
	ds_read_b128 v[78:81], v1 offset:45408
	ds_read_b128 v[82:85], v1 offset:45424
	ds_read_b128 v[86:89], v1 offset:45440
	s_waitcnt lgkmcnt(0)
	v_fmac_f32_e32 v19, v43, v18
	v_pk_fma_f32 v[20:21], v[44:45], v[18:19], v[20:21] op_sel:[0,0,0] op_sel_hi:[1,0,1]
	v_pk_fma_f32 v[22:23], v[46:47], v[18:19], v[22:23] op_sel:[0,0,0] op_sel_hi:[1,0,1]
	v_pk_fma_f32 v[24:25], v[48:49], v[18:19], v[24:25] op_sel:[0,0,0] op_sel_hi:[1,0,1]
	v_pk_fma_f32 v[26:27], v[50:51], v[18:19], v[26:27] op_sel:[0,0,0] op_sel_hi:[1,0,1]
	v_pk_fma_f32 v[28:29], v[52:53], v[18:19], v[28:29] op_sel:[0,0,0] op_sel_hi:[1,0,1]
	v_pk_fma_f32 v[30:31], v[54:55], v[18:19], v[30:31] op_sel:[0,0,0] op_sel_hi:[1,0,1]
	v_pk_fma_f32 v[32:33], v[56:57], v[18:19], v[32:33] op_sel:[0,0,0] op_sel_hi:[1,0,1]
	v_pk_fma_f32 v[34:35], v[58:59], v[18:19], v[34:35] op_sel:[0,0,0] op_sel_hi:[1,0,1]
	v_pk_fma_f32 v[36:37], v[60:61], v[18:19], v[36:37] op_sel:[0,0,0] op_sel_hi:[1,0,1]
	v_pk_fma_f32 v[38:39], v[62:63], v[18:19], v[38:39] op_sel:[0,0,0] op_sel_hi:[1,0,1]
	v_pk_fma_f32 v[40:41], v[64:65], v[18:19], v[40:41] op_sel:[0,0,0] op_sel_hi:[1,0,1]
	v_pk_fma_f32 v[20:21], v[68:69], v[18:19], v[20:21] op_sel:[0,1,0] op_sel_hi:[1,1,1]
	v_pk_fma_f32 v[22:23], v[70:71], v[18:19], v[22:23] op_sel:[0,1,0] op_sel_hi:[1,1,1]
	v_pk_fma_f32 v[24:25], v[72:73], v[18:19], v[24:25] op_sel:[0,1,0] op_sel_hi:[1,1,1]
	v_pk_fma_f32 v[26:27], v[74:75], v[18:19], v[26:27] op_sel:[0,1,0] op_sel_hi:[1,1,1]
	v_pk_fma_f32 v[28:29], v[76:77], v[18:19], v[28:29] op_sel:[0,1,0] op_sel_hi:[1,1,1]
	v_pk_fma_f32 v[30:31], v[78:79], v[18:19], v[30:31] op_sel:[0,1,0] op_sel_hi:[1,1,1]
	v_pk_fma_f32 v[32:33], v[80:81], v[18:19], v[32:33] op_sel:[0,1,0] op_sel_hi:[1,1,1]
	v_pk_fma_f32 v[34:35], v[82:83], v[18:19], v[34:35] op_sel:[0,1,0] op_sel_hi:[1,1,1]
	v_pk_fma_f32 v[36:37], v[84:85], v[18:19], v[36:37] op_sel:[0,1,0] op_sel_hi:[1,1,1]
	v_pk_fma_f32 v[38:39], v[86:87], v[18:19], v[38:39] op_sel:[0,1,0] op_sel_hi:[1,1,1]
	v_pk_fma_f32 v[40:41], v[88:89], v[18:19], v[40:41] op_sel:[0,1,0] op_sel_hi:[1,1,1]
	ds_read_b128 v[42:45], v1 offset:45504
	ds_read_b128 v[46:49], v1 offset:45520
	ds_read_b128 v[50:53], v1 offset:45536
	ds_read_b128 v[54:57], v1 offset:45552
	ds_read_b128 v[58:61], v1 offset:45568
	ds_read_b128 v[62:65], v1 offset:45584
	ds_read_b128 v[66:69], v1 offset:45664
	ds_read_b128 v[70:73], v1 offset:45680
	ds_read_b128 v[74:77], v1 offset:45696
	ds_read_b128 v[78:81], v1 offset:45712
	ds_read_b128 v[82:85], v1 offset:45728
	s_waitcnt lgkmcnt(0)
	v_fmac_f32_e32 v21, v45, v20
	v_pk_fma_f32 v[22:23], v[46:47], v[20:21], v[22:23] op_sel:[0,0,0] op_sel_hi:[1,0,1]
	v_pk_fma_f32 v[24:25], v[48:49], v[20:21], v[24:25] op_sel:[0,0,0] op_sel_hi:[1,0,1]
	v_pk_fma_f32 v[26:27], v[50:51], v[20:21], v[26:27] op_sel:[0,0,0] op_sel_hi:[1,0,1]
	v_pk_fma_f32 v[28:29], v[52:53], v[20:21], v[28:29] op_sel:[0,0,0] op_sel_hi:[1,0,1]
	v_pk_fma_f32 v[30:31], v[54:55], v[20:21], v[30:31] op_sel:[0,0,0] op_sel_hi:[1,0,1]
	v_pk_fma_f32 v[32:33], v[56:57], v[20:21], v[32:33] op_sel:[0,0,0] op_sel_hi:[1,0,1]
	v_pk_fma_f32 v[34:35], v[58:59], v[20:21], v[34:35] op_sel:[0,0,0] op_sel_hi:[1,0,1]
	v_pk_fma_f32 v[36:37], v[60:61], v[20:21], v[36:37] op_sel:[0,0,0] op_sel_hi:[1,0,1]
	v_pk_fma_f32 v[38:39], v[62:63], v[20:21], v[38:39] op_sel:[0,0,0] op_sel_hi:[1,0,1]
	v_pk_fma_f32 v[40:41], v[64:65], v[20:21], v[40:41] op_sel:[0,0,0] op_sel_hi:[1,0,1]
	v_pk_fma_f32 v[22:23], v[66:67], v[20:21], v[22:23] op_sel:[0,1,0] op_sel_hi:[1,1,1]
	v_pk_fma_f32 v[24:25], v[68:69], v[20:21], v[24:25] op_sel:[0,1,0] op_sel_hi:[1,1,1]
	v_pk_fma_f32 v[26:27], v[70:71], v[20:21], v[26:27] op_sel:[0,1,0] op_sel_hi:[1,1,1]
	v_pk_fma_f32 v[28:29], v[72:73], v[20:21], v[28:29] op_sel:[0,1,0] op_sel_hi:[1,1,1]
	v_pk_fma_f32 v[30:31], v[74:75], v[20:21], v[30:31] op_sel:[0,1,0] op_sel_hi:[1,1,1]
	v_pk_fma_f32 v[32:33], v[76:77], v[20:21], v[32:33] op_sel:[0,1,0] op_sel_hi:[1,1,1]
	v_pk_fma_f32 v[34:35], v[78:79], v[20:21], v[34:35] op_sel:[0,1,0] op_sel_hi:[1,1,1]
	v_pk_fma_f32 v[36:37], v[80:81], v[20:21], v[36:37] op_sel:[0,1,0] op_sel_hi:[1,1,1]
	v_pk_fma_f32 v[38:39], v[82:83], v[20:21], v[38:39] op_sel:[0,1,0] op_sel_hi:[1,1,1]
	v_pk_fma_f32 v[40:41], v[84:85], v[20:21], v[40:41] op_sel:[0,1,0] op_sel_hi:[1,1,1]
	ds_read_b128 v[42:45], v1 offset:45808
	ds_read_b128 v[46:49], v1 offset:45824
	ds_read_b128 v[50:53], v1 offset:45840
	ds_read_b128 v[54:57], v1 offset:45856
	ds_read_b128 v[58:61], v1 offset:45872
	ds_read_b128 v[62:65], v1 offset:45952
	ds_read_b128 v[66:69], v1 offset:45968
	ds_read_b128 v[70:73], v1 offset:45984
	ds_read_b128 v[74:77], v1 offset:46000
	ds_read_b128 v[78:81], v1 offset:46016
	s_waitcnt lgkmcnt(0)
	v_fmac_f32_e32 v23, v43, v22
	v_pk_fma_f32 v[24:25], v[44:45], v[22:23], v[24:25] op_sel:[0,0,0] op_sel_hi:[1,0,1]
	v_pk_fma_f32 v[26:27], v[46:47], v[22:23], v[26:27] op_sel:[0,0,0] op_sel_hi:[1,0,1]
	v_pk_fma_f32 v[28:29], v[48:49], v[22:23], v[28:29] op_sel:[0,0,0] op_sel_hi:[1,0,1]
	v_pk_fma_f32 v[30:31], v[50:51], v[22:23], v[30:31] op_sel:[0,0,0] op_sel_hi:[1,0,1]
	v_pk_fma_f32 v[32:33], v[52:53], v[22:23], v[32:33] op_sel:[0,0,0] op_sel_hi:[1,0,1]
	v_pk_fma_f32 v[34:35], v[54:55], v[22:23], v[34:35] op_sel:[0,0,0] op_sel_hi:[1,0,1]
	v_pk_fma_f32 v[36:37], v[56:57], v[22:23], v[36:37] op_sel:[0,0,0] op_sel_hi:[1,0,1]
	v_pk_fma_f32 v[38:39], v[58:59], v[22:23], v[38:39] op_sel:[0,0,0] op_sel_hi:[1,0,1]
	v_pk_fma_f32 v[40:41], v[60:61], v[22:23], v[40:41] op_sel:[0,0,0] op_sel_hi:[1,0,1]
	v_pk_fma_f32 v[24:25], v[64:65], v[22:23], v[24:25] op_sel:[0,1,0] op_sel_hi:[1,1,1]
	v_pk_fma_f32 v[26:27], v[66:67], v[22:23], v[26:27] op_sel:[0,1,0] op_sel_hi:[1,1,1]
	v_pk_fma_f32 v[28:29], v[68:69], v[22:23], v[28:29] op_sel:[0,1,0] op_sel_hi:[1,1,1]
	v_pk_fma_f32 v[30:31], v[70:71], v[22:23], v[30:31] op_sel:[0,1,0] op_sel_hi:[1,1,1]
	v_pk_fma_f32 v[32:33], v[72:73], v[22:23], v[32:33] op_sel:[0,1,0] op_sel_hi:[1,1,1]
	v_pk_fma_f32 v[34:35], v[74:75], v[22:23], v[34:35] op_sel:[0,1,0] op_sel_hi:[1,1,1]
	v_pk_fma_f32 v[36:37], v[76:77], v[22:23], v[36:37] op_sel:[0,1,0] op_sel_hi:[1,1,1]
	v_pk_fma_f32 v[38:39], v[78:79], v[22:23], v[38:39] op_sel:[0,1,0] op_sel_hi:[1,1,1]
	v_pk_fma_f32 v[40:41], v[80:81], v[22:23], v[40:41] op_sel:[0,1,0] op_sel_hi:[1,1,1]
	ds_read_b128 v[42:45], v1 offset:46096
	ds_read_b128 v[46:49], v1 offset:46112
	ds_read_b128 v[50:53], v1 offset:46128
	ds_read_b128 v[54:57], v1 offset:46144
	ds_read_b128 v[58:61], v1 offset:46160
	ds_read_b128 v[62:65], v1 offset:46256
	ds_read_b128 v[66:69], v1 offset:46272
	ds_read_b128 v[70:73], v1 offset:46288
	ds_read_b128 v[74:77], v1 offset:46304
	s_waitcnt lgkmcnt(0)
	v_fmac_f32_e32 v25, v45, v24
	v_pk_fma_f32 v[26:27], v[46:47], v[24:25], v[26:27] op_sel:[0,0,0] op_sel_hi:[1,0,1]
	v_pk_fma_f32 v[28:29], v[48:49], v[24:25], v[28:29] op_sel:[0,0,0] op_sel_hi:[1,0,1]
	v_pk_fma_f32 v[30:31], v[50:51], v[24:25], v[30:31] op_sel:[0,0,0] op_sel_hi:[1,0,1]
	v_pk_fma_f32 v[32:33], v[52:53], v[24:25], v[32:33] op_sel:[0,0,0] op_sel_hi:[1,0,1]
	v_pk_fma_f32 v[34:35], v[54:55], v[24:25], v[34:35] op_sel:[0,0,0] op_sel_hi:[1,0,1]
	v_pk_fma_f32 v[36:37], v[56:57], v[24:25], v[36:37] op_sel:[0,0,0] op_sel_hi:[1,0,1]
	v_pk_fma_f32 v[38:39], v[58:59], v[24:25], v[38:39] op_sel:[0,0,0] op_sel_hi:[1,0,1]
	v_pk_fma_f32 v[40:41], v[60:61], v[24:25], v[40:41] op_sel:[0,0,0] op_sel_hi:[1,0,1]
	v_pk_fma_f32 v[26:27], v[62:63], v[24:25], v[26:27] op_sel:[0,1,0] op_sel_hi:[1,1,1]
	v_pk_fma_f32 v[28:29], v[64:65], v[24:25], v[28:29] op_sel:[0,1,0] op_sel_hi:[1,1,1]
	v_pk_fma_f32 v[30:31], v[66:67], v[24:25], v[30:31] op_sel:[0,1,0] op_sel_hi:[1,1,1]
	v_pk_fma_f32 v[32:33], v[68:69], v[24:25], v[32:33] op_sel:[0,1,0] op_sel_hi:[1,1,1]
	v_pk_fma_f32 v[34:35], v[70:71], v[24:25], v[34:35] op_sel:[0,1,0] op_sel_hi:[1,1,1]
	v_pk_fma_f32 v[36:37], v[72:73], v[24:25], v[36:37] op_sel:[0,1,0] op_sel_hi:[1,1,1]
	v_pk_fma_f32 v[38:39], v[74:75], v[24:25], v[38:39] op_sel:[0,1,0] op_sel_hi:[1,1,1]
	v_pk_fma_f32 v[40:41], v[76:77], v[24:25], v[40:41] op_sel:[0,1,0] op_sel_hi:[1,1,1]
	ds_read_b128 v[42:45], v1 offset:46400
	ds_read_b128 v[46:49], v1 offset:46416
	ds_read_b128 v[50:53], v1 offset:46432
	ds_read_b128 v[54:57], v1 offset:46448
	ds_read_b128 v[58:61], v1 offset:46544
	ds_read_b128 v[62:65], v1 offset:46560
	ds_read_b128 v[66:69], v1 offset:46576
	ds_read_b128 v[70:73], v1 offset:46592
	ds_read_b128 v[74:77], v1 offset:46688
	ds_read_b128 v[78:81], v1 offset:46704
	ds_read_b128 v[82:85], v1 offset:46720
	ds_read_b128 v[86:89], v1 offset:46736
	ds_read_b128 v[226:229], v1 offset:46848
	ds_read_b128 v[230:233], v1 offset:46864
	ds_read_b128 v[234:237], v1 offset:46880
	s_waitcnt lgkmcnt(0)
	v_fmac_f32_e32 v27, v43, v26
	v_pk_fma_f32 v[28:29], v[44:45], v[26:27], v[28:29] op_sel:[0,0,0] op_sel_hi:[1,0,1]
	v_pk_fma_f32 v[30:31], v[46:47], v[26:27], v[30:31] op_sel:[0,0,0] op_sel_hi:[1,0,1]
	v_pk_fma_f32 v[32:33], v[48:49], v[26:27], v[32:33] op_sel:[0,0,0] op_sel_hi:[1,0,1]
	v_pk_fma_f32 v[34:35], v[50:51], v[26:27], v[34:35] op_sel:[0,0,0] op_sel_hi:[1,0,1]
	v_pk_fma_f32 v[36:37], v[52:53], v[26:27], v[36:37] op_sel:[0,0,0] op_sel_hi:[1,0,1]
	v_pk_fma_f32 v[38:39], v[54:55], v[26:27], v[38:39] op_sel:[0,0,0] op_sel_hi:[1,0,1]
	v_pk_fma_f32 v[40:41], v[56:57], v[26:27], v[40:41] op_sel:[0,0,0] op_sel_hi:[1,0,1]
	v_pk_fma_f32 v[28:29], v[60:61], v[26:27], v[28:29] op_sel:[0,1,0] op_sel_hi:[1,1,1]
	v_pk_fma_f32 v[30:31], v[62:63], v[26:27], v[30:31] op_sel:[0,1,0] op_sel_hi:[1,1,1]
	v_pk_fma_f32 v[32:33], v[64:65], v[26:27], v[32:33] op_sel:[0,1,0] op_sel_hi:[1,1,1]
	v_pk_fma_f32 v[34:35], v[66:67], v[26:27], v[34:35] op_sel:[0,1,0] op_sel_hi:[1,1,1]
	v_pk_fma_f32 v[36:37], v[68:69], v[26:27], v[36:37] op_sel:[0,1,0] op_sel_hi:[1,1,1]
	v_pk_fma_f32 v[38:39], v[70:71], v[26:27], v[38:39] op_sel:[0,1,0] op_sel_hi:[1,1,1]
	v_pk_fma_f32 v[40:41], v[72:73], v[26:27], v[40:41] op_sel:[0,1,0] op_sel_hi:[1,1,1]
	v_fmac_f32_e32 v29, v77, v28
	v_pk_fma_f32 v[30:31], v[78:79], v[28:29], v[30:31] op_sel:[0,0,0] op_sel_hi:[1,0,1]
	v_pk_fma_f32 v[32:33], v[80:81], v[28:29], v[32:33] op_sel:[0,0,0] op_sel_hi:[1,0,1]
	v_pk_fma_f32 v[34:35], v[82:83], v[28:29], v[34:35] op_sel:[0,0,0] op_sel_hi:[1,0,1]
	v_pk_fma_f32 v[36:37], v[84:85], v[28:29], v[36:37] op_sel:[0,0,0] op_sel_hi:[1,0,1]
	v_pk_fma_f32 v[38:39], v[86:87], v[28:29], v[38:39] op_sel:[0,0,0] op_sel_hi:[1,0,1]
	v_pk_fma_f32 v[40:41], v[88:89], v[28:29], v[40:41] op_sel:[0,0,0] op_sel_hi:[1,0,1]
	v_pk_fma_f32 v[30:31], v[226:227], v[28:29], v[30:31] op_sel:[0,1,0] op_sel_hi:[1,1,1]
	v_pk_fma_f32 v[32:33], v[228:229], v[28:29], v[32:33] op_sel:[0,1,0] op_sel_hi:[1,1,1]
	v_pk_fma_f32 v[34:35], v[230:231], v[28:29], v[34:35] op_sel:[0,1,0] op_sel_hi:[1,1,1]
	v_pk_fma_f32 v[36:37], v[232:233], v[28:29], v[36:37] op_sel:[0,1,0] op_sel_hi:[1,1,1]
	v_pk_fma_f32 v[38:39], v[234:235], v[28:29], v[38:39] op_sel:[0,1,0] op_sel_hi:[1,1,1]
	v_pk_fma_f32 v[40:41], v[236:237], v[28:29], v[40:41] op_sel:[0,1,0] op_sel_hi:[1,1,1]
	ds_read_b128 v[42:45], v1 offset:46992
	ds_read_b128 v[46:49], v1 offset:47008
	ds_read_b128 v[50:53], v1 offset:47024
	ds_read_b128 v[54:57], v1 offset:47136
	ds_read_b128 v[58:61], v1 offset:47152
	ds_read_b128 v[62:65], v1 offset:47168
	ds_read_b128 v[66:69], v1 offset:47280
	ds_read_b128 v[70:73], v1 offset:47296
	ds_read_b128 v[74:77], v1 offset:47312
	ds_read_b128 v[78:81], v1 offset:47440
	ds_read_b128 v[82:85], v1 offset:47456
	ds_read_b128 v[86:89], v1 offset:47584
	ds_read_b128 v[226:229], v1 offset:47600
	ds_read_b128 v[230:233], v1 offset:47728
	ds_read_b128 v[234:237], v1 offset:47744
	s_waitcnt lgkmcnt(0)
	v_fmac_f32_e32 v31, v43, v30
	v_pk_fma_f32 v[32:33], v[44:45], v[30:31], v[32:33] op_sel:[0,0,0] op_sel_hi:[1,0,1]
	v_pk_fma_f32 v[34:35], v[46:47], v[30:31], v[34:35] op_sel:[0,0,0] op_sel_hi:[1,0,1]
	v_pk_fma_f32 v[36:37], v[48:49], v[30:31], v[36:37] op_sel:[0,0,0] op_sel_hi:[1,0,1]
	v_pk_fma_f32 v[38:39], v[50:51], v[30:31], v[38:39] op_sel:[0,0,0] op_sel_hi:[1,0,1]
	v_pk_fma_f32 v[40:41], v[52:53], v[30:31], v[40:41] op_sel:[0,0,0] op_sel_hi:[1,0,1]
	v_pk_fma_f32 v[32:33], v[56:57], v[30:31], v[32:33] op_sel:[0,1,0] op_sel_hi:[1,1,1]
	v_pk_fma_f32 v[34:35], v[58:59], v[30:31], v[34:35] op_sel:[0,1,0] op_sel_hi:[1,1,1]
	v_pk_fma_f32 v[36:37], v[60:61], v[30:31], v[36:37] op_sel:[0,1,0] op_sel_hi:[1,1,1]
	v_pk_fma_f32 v[38:39], v[62:63], v[30:31], v[38:39] op_sel:[0,1,0] op_sel_hi:[1,1,1]
	v_pk_fma_f32 v[40:41], v[64:65], v[30:31], v[40:41] op_sel:[0,1,0] op_sel_hi:[1,1,1]
	v_fmac_f32_e32 v33, v69, v32
	v_pk_fma_f32 v[34:35], v[70:71], v[32:33], v[34:35] op_sel:[0,0,0] op_sel_hi:[1,0,1]
	v_pk_fma_f32 v[36:37], v[72:73], v[32:33], v[36:37] op_sel:[0,0,0] op_sel_hi:[1,0,1]
	v_pk_fma_f32 v[38:39], v[74:75], v[32:33], v[38:39] op_sel:[0,0,0] op_sel_hi:[1,0,1]
	v_pk_fma_f32 v[40:41], v[76:77], v[32:33], v[40:41] op_sel:[0,0,0] op_sel_hi:[1,0,1]
	v_pk_fma_f32 v[34:35], v[78:79], v[32:33], v[34:35] op_sel:[0,1,0] op_sel_hi:[1,1,1]
	v_pk_fma_f32 v[36:37], v[80:81], v[32:33], v[36:37] op_sel:[0,1,0] op_sel_hi:[1,1,1]
	v_pk_fma_f32 v[38:39], v[82:83], v[32:33], v[38:39] op_sel:[0,1,0] op_sel_hi:[1,1,1]
	v_pk_fma_f32 v[40:41], v[84:85], v[32:33], v[40:41] op_sel:[0,1,0] op_sel_hi:[1,1,1]
	v_fmac_f32_e32 v35, v87, v34
	v_pk_fma_f32 v[36:37], v[88:89], v[34:35], v[36:37] op_sel:[0,0,0] op_sel_hi:[1,0,1]
	v_pk_fma_f32 v[38:39], v[226:227], v[34:35], v[38:39] op_sel:[0,0,0] op_sel_hi:[1,0,1]
	v_pk_fma_f32 v[40:41], v[228:229], v[34:35], v[40:41] op_sel:[0,0,0] op_sel_hi:[1,0,1]
	v_pk_fma_f32 v[36:37], v[232:233], v[34:35], v[36:37] op_sel:[0,1,0] op_sel_hi:[1,1,1]
	v_pk_fma_f32 v[38:39], v[234:235], v[34:35], v[38:39] op_sel:[0,1,0] op_sel_hi:[1,1,1]
	v_pk_fma_f32 v[40:41], v[236:237], v[34:35], v[40:41] op_sel:[0,1,0] op_sel_hi:[1,1,1]
	ds_read_b128 v[42:45], v1 offset:47872
	ds_read_b128 v[46:49], v1 offset:47888
	ds_read_b128 v[50:53], v1 offset:48032
	ds_read_b128 v[54:57], v1 offset:48176
	ds_read_b128 v[58:61], v1 offset:48320
	ds_read_b128 v[62:65], v1 offset:48464
	s_waitcnt lgkmcnt(0)
	v_fmac_f32_e32 v37, v45, v36
	v_pk_fma_f32 v[38:39], v[46:47], v[36:37], v[38:39] op_sel:[0,0,0] op_sel_hi:[1,0,1]
	v_pk_fma_f32 v[40:41], v[48:49], v[36:37], v[40:41] op_sel:[0,0,0] op_sel_hi:[1,0,1]
	v_pk_fma_f32 v[38:39], v[50:51], v[36:37], v[38:39] op_sel:[0,1,0] op_sel_hi:[1,1,1]
	v_pk_fma_f32 v[40:41], v[52:53], v[36:37], v[40:41] op_sel:[0,1,0] op_sel_hi:[1,1,1]
	v_fmac_f32_e32 v39, v55, v38
	v_pk_fma_f32 v[40:41], v[56:57], v[38:39], v[40:41] op_sel:[0,0,0] op_sel_hi:[1,0,1]
	v_pk_fma_f32 v[40:41], v[60:61], v[38:39], v[40:41] op_sel:[0,1,0] op_sel_hi:[1,1,1]
	v_fmac_f32_e32 v41, v65, v40
	ds_write_b32 v135, v10 offset:57856
	ds_write_b32 v135, v11 offset:58000
	ds_write_b32 v135, v12 offset:58144
	ds_write_b32 v135, v13 offset:58288
	ds_write_b32 v135, v14 offset:58432
	ds_write_b32 v135, v15 offset:58576
	ds_write_b32 v135, v16 offset:58720
	ds_write_b32 v135, v17 offset:58864
	ds_write_b32 v135, v18 offset:59008
	ds_write_b32 v135, v19 offset:59152
	ds_write_b32 v135, v20 offset:59296
	ds_write_b32 v135, v21 offset:59440
	ds_write_b32 v135, v22 offset:59584
	ds_write_b32 v135, v23 offset:59728
	ds_write_b32 v135, v24 offset:59872
	ds_write_b32 v135, v25 offset:60016
	ds_write_b32 v135, v26 offset:60160
	ds_write_b32 v135, v27 offset:60304
	ds_write_b32 v135, v28 offset:60448
	ds_write_b32 v135, v29 offset:60592
	ds_write_b32 v135, v30 offset:60736
	ds_write_b32 v135, v31 offset:60880
	ds_write_b32 v135, v32 offset:61024
	ds_write_b32 v135, v33 offset:61168
	ds_write_b32 v135, v34 offset:61312
	ds_write_b32 v135, v35 offset:61456
	ds_write_b32 v135, v36 offset:61600
	ds_write_b32 v135, v37 offset:61744
	ds_write_b32 v135, v38 offset:61888
	ds_write_b32 v135, v39 offset:62032
	ds_write_b32 v135, v40 offset:62176
	ds_write_b32 v135, v41 offset:62320
	s_branch .Ldc_b3
